# unit_scan chunk loop: LDS fragment reads of the MFMA section issued two k-steps ahead with counted lgkmcnt
# speedup vs baseline: 1.0060x; 1.0060x over previous
.Lscan_nopf:
	v_and_b32_e32 v17, 0xffff, v42
	v_lshrrev_b32_e32 v42, 16, v42
	v_lshl_or_b32 v17, v46, 16, v17
	v_and_or_b32 v42, v46, s59, v42
	v_add_u32_e32 v46, 0x8800, v51
	ds_write2_b32 v46, v17, v42 offset1:68
	v_and_b32_e32 v17, 0xffff, v43
	v_lshrrev_b32_e32 v42, 16, v43
	v_lshl_or_b32 v17, v47, 16, v17
	v_and_or_b32 v42, v47, s59, v42
	ds_write2_b32 v46, v17, v42 offset0:136 offset1:204
	v_and_b32_e32 v17, 0xffff, v44
	v_lshrrev_b32_e32 v42, 16, v44
	v_lshl_or_b32 v17, v48, 16, v17
	v_and_or_b32 v42, v48, s59, v42
	v_add_u32_e32 v43, 0x8c00, v51
	ds_write2_b32 v43, v17, v42 offset0:16 offset1:84
	v_and_b32_e32 v17, 0xffff, v45
	v_lshrrev_b32_e32 v42, 16, v45
	v_lshl_or_b32 v17, v49, 16, v17
	v_and_or_b32 v42, v49, s59, v42
	ds_write2_b32 v43, v17, v42 offset0:152 offset1:220
	s_waitcnt lgkmcnt(0)
	s_barrier
	ds_read_b128 v[132:135], v174
	ds_read_b128 v[136:139], v174 offset:64
	ds_read_b128 v[140:143], v174 offset:128
	ds_read_b128 v[144:147], v174 offset:192
	v_mov_b32_e32 v17, v16
	v_pk_mul_f32 v[2:3], v[16:17], v[2:3]
	v_pk_mul_f32 v[6:7], v[16:17], v[6:7]
	v_pk_mul_f32 v[10:11], v[16:17], v[10:11]
	v_pk_mul_f32 v[46:47], v[16:17], v[14:15]
	v_add_u32_e32 v17, v103, v105
	v_pk_mul_f32 v[44:45], v[26:27], v[12:13]
	v_add_u32_e32 v42, v103, v107
	ds_read_b128 v[194:197], v17 offset:34816
	ds_read_b128 v[198:201], v17 offset:39168
	ds_read_b128 v[202:205], v17 offset:43520
	ds_read_b128 v[206:209], v42 offset:34816
	ds_read_b128 v[210:213], v17 offset:34880
	ds_read_b128 v[214:217], v17 offset:39232
	ds_read_b128 v[218:221], v17 offset:43584
	ds_read_b128 v[148:151], v42 offset:34880
	s_waitcnt lgkmcnt(4)
	v_mfma_f32_16x16x32_bf16 v[0:3], v[132:135], v[194:197], v[0:3]
	v_mfma_f32_16x16x32_bf16 v[4:7], v[132:135], v[198:201], v[4:7]
	v_mfma_f32_16x16x32_bf16 v[8:11], v[132:135], v[202:205], v[8:11]
	v_mfma_f32_16x16x32_bf16 v[12:15], v[132:135], v[206:209], v[44:47]
	ds_read_b128 v[194:197], v17 offset:34944
	ds_read_b128 v[198:201], v17 offset:39296
	ds_read_b128 v[202:205], v17 offset:43648
	ds_read_b128 v[206:209], v42 offset:34944
	s_waitcnt lgkmcnt(4)
	v_mfma_f32_16x16x32_bf16 v[0:3], v[136:139], v[210:213], v[0:3]
	v_mfma_f32_16x16x32_bf16 v[4:7], v[136:139], v[214:217], v[4:7]
	v_mfma_f32_16x16x32_bf16 v[8:11], v[136:139], v[218:221], v[8:11]
	v_mfma_f32_16x16x32_bf16 v[12:15], v[136:139], v[148:151], v[12:15]
	ds_read_b128 v[210:213], v17 offset:35008
	ds_read_b128 v[214:217], v17 offset:39360
	ds_read_b128 v[218:221], v17 offset:43712
	ds_read_b128 v[148:151], v42 offset:35008
	s_waitcnt lgkmcnt(4)
	v_mfma_f32_16x16x32_bf16 v[0:3], v[140:143], v[194:197], v[0:3]
	v_mfma_f32_16x16x32_bf16 v[4:7], v[140:143], v[198:201], v[4:7]
	v_mfma_f32_16x16x32_bf16 v[8:11], v[140:143], v[202:205], v[8:11]
	v_mfma_f32_16x16x32_bf16 v[12:15], v[140:143], v[206:209], v[12:15]
	s_waitcnt lgkmcnt(0)
	v_mfma_f32_16x16x32_bf16 v[0:3], v[144:147], v[210:213], v[0:3]
	v_mfma_f32_16x16x32_bf16 v[4:7], v[144:147], v[214:217], v[4:7]
	v_mfma_f32_16x16x32_bf16 v[8:11], v[144:147], v[218:221], v[8:11]
	v_mfma_f32_16x16x32_bf16 v[12:15], v[144:147], v[148:151], v[12:15]
	s_nop 1
	s_cbranch_scc1 .LBB0_309
	s_lshl_b32 s4, s65, 2
	s_or_b32 s52, s4, s0
	s_ashr_i32 s53, s52, 31
	s_lshl_b64 s[52:53], s[52:53], 17
	s_add_u32 s10, s10, s52
	v_lshlrev_b32_e32 v16, 2, v68
	s_addc_u32 s11, s11, s53
	v_lshl_or_b32 v152, s64, 8, v16
	v_lshl_add_u64 v[16:17], s[10:11], 0, v[152:153]
	s_mov_b64 s[10:11], 0x6400000
	v_lshl_add_u64 v[16:17], v[16:17], 0, s[10:11]
	v_lshl_add_u64 v[18:19], v[16:17], 0, v[112:113]
	v_lshl_add_u64 v[20:21], v[16:17], 0, v[114:115]
	v_readlane_b32 s92, v254, 25
	v_readlane_b32 s84, v254, 51
	flat_store_dword v[18:19], v0
	flat_store_dword v[20:21], v1
	v_lshl_add_u64 v[0:1], v[16:17], 0, v[116:117]
	v_lshl_add_u64 v[16:17], v[16:17], 0, v[118:119]
	v_readlane_b32 s93, v254, 26
	v_readlane_b32 s94, v254, 27
	v_readlane_b32 s95, v254, 28
	v_readlane_b32 s85, v254, 52
	flat_store_dword v[0:1], v2
	flat_store_dword v[16:17], v3
	flat_store_dword v[18:19], v4 offset:64
	flat_store_dword v[20:21], v5 offset:64
	flat_store_dword v[0:1], v6 offset:64
	flat_store_dword v[16:17], v7 offset:64
	flat_store_dword v[18:19], v8 offset:128
	flat_store_dword v[20:21], v9 offset:128
	flat_store_dword v[0:1], v10 offset:128
	flat_store_dword v[16:17], v11 offset:128
	flat_store_dword v[18:19], v12 offset:192
	flat_store_dword v[20:21], v13 offset:192
	flat_store_dword v[0:1], v14 offset:192
	flat_store_dword v[16:17], v15 offset:192
	s_branch .LBB0_281
